# adaLN modulation GEMV (phase 0): weight-row loads double-buffered, 16 per k-block issued one block ahead with counted vmcnt (was <=8 in flight, vmcnt(0) each block)
# baseline (speedup 1.0000x reference)
; #define LAS __attribute__((address_space(3)))
; __device__ __forceinline__ void phase0(CArgsP a, int l, LAS unsigned char* lds) {
;     ...
;         for (int item = blockIdx.x; item < 768; item += G) {
;             const int ll = item / 384, n0 = (item % 384) * 32, kbase = wave * 256;
;             const float* W = a->in[I_WMOD] + (size_t)ll * 2048 * 12288 + n0 + l32 + (size_t)(kbase + half) * 12288;
;             const LAS float* Sp = S + (kbase + half) * 17 + vv;
;             f32x16 acc = f32x16{};
; #pragma unroll 16
;             for (int i = 0; i < 128; ++i) acc = __builtin_amdgcn_mfma_f32_32x32x2f32(Sp[i * 34], __builtin_nontemporal_load(W + (size_t)i * 2 * 12288), acc, 0, 0, 0);
.LBB0_29:
	s_mul_hi_i32 s29, s18, 0x2aaaaaab
	s_lshr_b32 s30, s29, 31
	s_ashr_i32 s29, s29, 6
	s_add_i32 s29, s29, s30
	s_mul_i32 s30, s29, 0x180
	s_sub_i32 s30, s18, s30
	s_lshl_b32 s30, s30, 5
	s_mul_i32 s34, s29, 0x6000000
	s_mul_hi_i32 s31, s29, 0x6000000
	s_waitcnt lgkmcnt(0)
	s_add_u32 s40, s16, s34
	s_addc_u32 s41, s17, s31
	s_ashr_i32 s31, s30, 31
	s_lshl_b64 s[34:35], s[30:31], 2
	s_add_u32 s34, s40, s34
	s_addc_u32 s35, s41, s35
	v_lshl_add_u64 v[0:1], s[34:35], 0, v[208:209]
	v_lshl_add_u64 v[24:25], v[0:1], 0, v[20:21]
	v_mov_b32_e32 v0, 0
	s_mov_b64 s[34:35], 0
	v_mov_b32_e32 v28, v19
	v_mov_b32_e32 v1, v0
	v_mov_b32_e32 v2, v0
	v_mov_b32_e32 v3, v0
	v_mov_b32_e32 v4, v0
	v_mov_b32_e32 v5, v0
	v_mov_b32_e32 v6, v0
	v_mov_b32_e32 v7, v0
	v_mov_b32_e32 v8, v0
	v_mov_b32_e32 v9, v0
	v_mov_b32_e32 v10, v0
	v_mov_b32_e32 v11, v0
	v_mov_b32_e32 v12, v0
	v_mov_b32_e32 v13, v0
	v_mov_b32_e32 v14, v0
	v_mov_b32_e32 v15, v0
	v_lshl_add_u64 v[102:103], v[24:25], 0, s[34:35]
	global_load_dword v54, v[102:103], off nt
	v_add_co_u32_e64 v102, s[44:45], s52, v102
	s_nop 1
	v_addc_co_u32_e64 v103, s[44:45], 0, v103, s[44:45]
	global_load_dword v55, v[102:103], off nt
	v_add_co_u32_e64 v102, s[44:45], s52, v102
	s_nop 1
	v_addc_co_u32_e64 v103, s[44:45], 0, v103, s[44:45]
	global_load_dword v56, v[102:103], off nt
	v_add_co_u32_e64 v102, s[44:45], s52, v102
	s_nop 1
	v_addc_co_u32_e64 v103, s[44:45], 0, v103, s[44:45]
	global_load_dword v57, v[102:103], off nt
	v_add_co_u32_e64 v102, s[44:45], s52, v102
	s_nop 1
	v_addc_co_u32_e64 v103, s[44:45], 0, v103, s[44:45]
	global_load_dword v58, v[102:103], off nt
	v_add_co_u32_e64 v102, s[44:45], s52, v102
	s_nop 1
	v_addc_co_u32_e64 v103, s[44:45], 0, v103, s[44:45]
	global_load_dword v59, v[102:103], off nt
	v_add_co_u32_e64 v102, s[44:45], s52, v102
	s_nop 1
	v_addc_co_u32_e64 v103, s[44:45], 0, v103, s[44:45]
	global_load_dword v60, v[102:103], off nt
	v_add_co_u32_e64 v102, s[44:45], s52, v102
	s_nop 1
	v_addc_co_u32_e64 v103, s[44:45], 0, v103, s[44:45]
	global_load_dword v61, v[102:103], off nt
	v_add_co_u32_e64 v102, s[44:45], s52, v102
	s_nop 1
	v_addc_co_u32_e64 v103, s[44:45], 0, v103, s[44:45]
	global_load_dword v62, v[102:103], off nt
	v_add_co_u32_e64 v102, s[44:45], s52, v102
	s_nop 1
	v_addc_co_u32_e64 v103, s[44:45], 0, v103, s[44:45]
	global_load_dword v63, v[102:103], off nt
	v_add_co_u32_e64 v102, s[44:45], s52, v102
	s_nop 1
	v_addc_co_u32_e64 v103, s[44:45], 0, v103, s[44:45]
	global_load_dword v64, v[102:103], off nt
	v_add_co_u32_e64 v102, s[44:45], s52, v102
	s_nop 1
	v_addc_co_u32_e64 v103, s[44:45], 0, v103, s[44:45]
	global_load_dword v65, v[102:103], off nt
	v_add_co_u32_e64 v102, s[44:45], s52, v102
	s_nop 1
	v_addc_co_u32_e64 v103, s[44:45], 0, v103, s[44:45]
	global_load_dword v66, v[102:103], off nt
	v_add_co_u32_e64 v102, s[44:45], s52, v102
	s_nop 1
	v_addc_co_u32_e64 v103, s[44:45], 0, v103, s[44:45]
	global_load_dword v67, v[102:103], off nt
	v_add_co_u32_e64 v102, s[44:45], s52, v102
	s_nop 1
	v_addc_co_u32_e64 v103, s[44:45], 0, v103, s[44:45]
	global_load_dword v68, v[102:103], off nt
	v_add_co_u32_e64 v102, s[44:45], s52, v102
	s_nop 1
	v_addc_co_u32_e64 v103, s[44:45], 0, v103, s[44:45]
	global_load_dword v69, v[102:103], off nt
	s_add_u32 s34, s34, 0x180000
	s_addc_u32 s35, s35, 0
.LBB0_30:
	v_lshl_add_u64 v[102:103], v[24:25], 0, s[34:35]
	global_load_dword v70, v[102:103], off nt
	v_add_co_u32_e64 v102, s[44:45], s52, v102
	s_nop 1
	v_addc_co_u32_e64 v103, s[44:45], 0, v103, s[44:45]
	global_load_dword v71, v[102:103], off nt
	v_add_co_u32_e64 v102, s[44:45], s52, v102
	s_nop 1
	v_addc_co_u32_e64 v103, s[44:45], 0, v103, s[44:45]
	global_load_dword v72, v[102:103], off nt
	v_add_co_u32_e64 v102, s[44:45], s52, v102
	s_nop 1
	v_addc_co_u32_e64 v103, s[44:45], 0, v103, s[44:45]
	global_load_dword v73, v[102:103], off nt
	v_add_co_u32_e64 v102, s[44:45], s52, v102
	s_nop 1
	v_addc_co_u32_e64 v103, s[44:45], 0, v103, s[44:45]
	global_load_dword v74, v[102:103], off nt
	v_add_co_u32_e64 v102, s[44:45], s52, v102
	s_nop 1
	v_addc_co_u32_e64 v103, s[44:45], 0, v103, s[44:45]
	global_load_dword v75, v[102:103], off nt
	v_add_co_u32_e64 v102, s[44:45], s52, v102
	s_nop 1
	v_addc_co_u32_e64 v103, s[44:45], 0, v103, s[44:45]
	global_load_dword v76, v[102:103], off nt
	v_add_co_u32_e64 v102, s[44:45], s52, v102
	s_nop 1
	v_addc_co_u32_e64 v103, s[44:45], 0, v103, s[44:45]
	global_load_dword v77, v[102:103], off nt
	v_add_co_u32_e64 v102, s[44:45], s52, v102
	s_nop 1
	v_addc_co_u32_e64 v103, s[44:45], 0, v103, s[44:45]
	global_load_dword v78, v[102:103], off nt
	v_add_co_u32_e64 v102, s[44:45], s52, v102
	s_nop 1
	v_addc_co_u32_e64 v103, s[44:45], 0, v103, s[44:45]
	global_load_dword v79, v[102:103], off nt
	v_add_co_u32_e64 v102, s[44:45], s52, v102
	s_nop 1
	v_addc_co_u32_e64 v103, s[44:45], 0, v103, s[44:45]
	global_load_dword v80, v[102:103], off nt
	v_add_co_u32_e64 v102, s[44:45], s52, v102
	s_nop 1
	v_addc_co_u32_e64 v103, s[44:45], 0, v103, s[44:45]
	global_load_dword v81, v[102:103], off nt
	v_add_co_u32_e64 v102, s[44:45], s52, v102
	s_nop 1
	v_addc_co_u32_e64 v103, s[44:45], 0, v103, s[44:45]
	global_load_dword v82, v[102:103], off nt
	v_add_co_u32_e64 v102, s[44:45], s52, v102
	s_nop 1
	v_addc_co_u32_e64 v103, s[44:45], 0, v103, s[44:45]
	global_load_dword v83, v[102:103], off nt
	v_add_co_u32_e64 v102, s[44:45], s52, v102
	s_nop 1
	v_addc_co_u32_e64 v103, s[44:45], 0, v103, s[44:45]
	global_load_dword v84, v[102:103], off nt
	v_add_co_u32_e64 v102, s[44:45], s52, v102
	s_nop 1
	v_addc_co_u32_e64 v103, s[44:45], 0, v103, s[44:45]
	global_load_dword v85, v[102:103], off nt
	s_add_u32 s34, s34, 0x180000
	s_addc_u32 s35, s35, 0
	ds_read2_b32 v[86:87], v28 offset1:34
	ds_read2_b32 v[88:89], v28 offset0:68 offset1:102
	ds_read2_b32 v[90:91], v28 offset0:136 offset1:170
	ds_read2_b32 v[92:93], v28 offset0:204 offset1:238
	v_add_u32_e32 v104, 0x400, v28
	ds_read2_b32 v[94:95], v104 offset0:16 offset1:50
	ds_read2_b32 v[96:97], v104 offset0:84 offset1:118
	ds_read2_b32 v[98:99], v104 offset0:152 offset1:186
	ds_read2_b32 v[100:101], v104 offset0:220 offset1:254
	v_add_u32_e32 v28, 0x880, v28
	s_waitcnt lgkmcnt(0)
; __device__ __forceinline__ void phase0(CArgsP a, int l, LAS unsigned char* lds) {
;     ...
; #pragma unroll 16
;             for (int i = 0; i < 128; ++i) acc = __builtin_amdgcn_mfma_f32_32x32x2f32(Sp[i * 34], __builtin_nontemporal_load(W + (size_t)i * 2 * 12288), acc, 0, 0, 0);
	s_waitcnt vmcnt(31)
	v_mfma_f32_32x32x2_f32 v[0:15], v86, v54, v[0:15]
	s_waitcnt vmcnt(30)
	v_mfma_f32_32x32x2_f32 v[0:15], v87, v55, v[0:15]
	s_waitcnt vmcnt(29)
	v_mfma_f32_32x32x2_f32 v[0:15], v88, v56, v[0:15]
	s_waitcnt vmcnt(28)
	v_mfma_f32_32x32x2_f32 v[0:15], v89, v57, v[0:15]
	s_waitcnt vmcnt(27)
	v_mfma_f32_32x32x2_f32 v[0:15], v90, v58, v[0:15]
	s_waitcnt vmcnt(26)
	v_mfma_f32_32x32x2_f32 v[0:15], v91, v59, v[0:15]
	s_waitcnt vmcnt(25)
	v_mfma_f32_32x32x2_f32 v[0:15], v92, v60, v[0:15]
	s_waitcnt vmcnt(24)
	v_mfma_f32_32x32x2_f32 v[0:15], v93, v61, v[0:15]
	s_waitcnt vmcnt(23)
	v_mfma_f32_32x32x2_f32 v[0:15], v94, v62, v[0:15]
	s_waitcnt vmcnt(22)
	v_mfma_f32_32x32x2_f32 v[0:15], v95, v63, v[0:15]
	s_waitcnt vmcnt(21)
	v_mfma_f32_32x32x2_f32 v[0:15], v96, v64, v[0:15]
	s_waitcnt vmcnt(20)
	v_mfma_f32_32x32x2_f32 v[0:15], v97, v65, v[0:15]
	s_waitcnt vmcnt(19)
	v_mfma_f32_32x32x2_f32 v[0:15], v98, v66, v[0:15]
	s_waitcnt vmcnt(18)
	v_mfma_f32_32x32x2_f32 v[0:15], v99, v67, v[0:15]
	s_waitcnt vmcnt(17)
	v_mfma_f32_32x32x2_f32 v[0:15], v100, v68, v[0:15]
	s_waitcnt vmcnt(16)
	v_mfma_f32_32x32x2_f32 v[0:15], v101, v69, v[0:15]
	v_lshl_add_u64 v[102:103], v[24:25], 0, s[34:35]
	global_load_dword v54, v[102:103], off nt
	v_add_co_u32_e64 v102, s[44:45], s52, v102
	s_nop 1
	v_addc_co_u32_e64 v103, s[44:45], 0, v103, s[44:45]
	global_load_dword v55, v[102:103], off nt
	v_add_co_u32_e64 v102, s[44:45], s52, v102
	s_nop 1
	v_addc_co_u32_e64 v103, s[44:45], 0, v103, s[44:45]
	global_load_dword v56, v[102:103], off nt
	v_add_co_u32_e64 v102, s[44:45], s52, v102
	s_nop 1
	v_addc_co_u32_e64 v103, s[44:45], 0, v103, s[44:45]
	global_load_dword v57, v[102:103], off nt
	v_add_co_u32_e64 v102, s[44:45], s52, v102
	s_nop 1
	v_addc_co_u32_e64 v103, s[44:45], 0, v103, s[44:45]
	global_load_dword v58, v[102:103], off nt
	v_add_co_u32_e64 v102, s[44:45], s52, v102
	s_nop 1
	v_addc_co_u32_e64 v103, s[44:45], 0, v103, s[44:45]
	global_load_dword v59, v[102:103], off nt
	v_add_co_u32_e64 v102, s[44:45], s52, v102
	s_nop 1
	v_addc_co_u32_e64 v103, s[44:45], 0, v103, s[44:45]
	global_load_dword v60, v[102:103], off nt
	v_add_co_u32_e64 v102, s[44:45], s52, v102
	s_nop 1
	v_addc_co_u32_e64 v103, s[44:45], 0, v103, s[44:45]
	global_load_dword v61, v[102:103], off nt
	v_add_co_u32_e64 v102, s[44:45], s52, v102
	s_nop 1
	v_addc_co_u32_e64 v103, s[44:45], 0, v103, s[44:45]
	global_load_dword v62, v[102:103], off nt
	v_add_co_u32_e64 v102, s[44:45], s52, v102
	s_nop 1
	v_addc_co_u32_e64 v103, s[44:45], 0, v103, s[44:45]
	global_load_dword v63, v[102:103], off nt
	v_add_co_u32_e64 v102, s[44:45], s52, v102
	s_nop 1
	v_addc_co_u32_e64 v103, s[44:45], 0, v103, s[44:45]
	global_load_dword v64, v[102:103], off nt
	v_add_co_u32_e64 v102, s[44:45], s52, v102
	s_nop 1
	v_addc_co_u32_e64 v103, s[44:45], 0, v103, s[44:45]
	global_load_dword v65, v[102:103], off nt
	v_add_co_u32_e64 v102, s[44:45], s52, v102
	s_nop 1
	v_addc_co_u32_e64 v103, s[44:45], 0, v103, s[44:45]
	global_load_dword v66, v[102:103], off nt
	v_add_co_u32_e64 v102, s[44:45], s52, v102
	s_nop 1
	v_addc_co_u32_e64 v103, s[44:45], 0, v103, s[44:45]
	global_load_dword v67, v[102:103], off nt
	v_add_co_u32_e64 v102, s[44:45], s52, v102
	s_nop 1
	v_addc_co_u32_e64 v103, s[44:45], 0, v103, s[44:45]
	global_load_dword v68, v[102:103], off nt
	v_add_co_u32_e64 v102, s[44:45], s52, v102
	s_nop 1
	v_addc_co_u32_e64 v103, s[44:45], 0, v103, s[44:45]
	global_load_dword v69, v[102:103], off nt
	s_add_u32 s34, s34, 0x180000
	s_addc_u32 s35, s35, 0
	ds_read2_b32 v[86:87], v28 offset1:34
	ds_read2_b32 v[88:89], v28 offset0:68 offset1:102
	ds_read2_b32 v[90:91], v28 offset0:136 offset1:170
	ds_read2_b32 v[92:93], v28 offset0:204 offset1:238
	v_add_u32_e32 v104, 0x400, v28
	ds_read2_b32 v[94:95], v104 offset0:16 offset1:50
	ds_read2_b32 v[96:97], v104 offset0:84 offset1:118
	ds_read2_b32 v[98:99], v104 offset0:152 offset1:186
	ds_read2_b32 v[100:101], v104 offset0:220 offset1:254
	v_add_u32_e32 v28, 0x880, v28
	s_waitcnt lgkmcnt(0)
	s_waitcnt vmcnt(31)
	v_mfma_f32_32x32x2_f32 v[0:15], v86, v70, v[0:15]
	s_waitcnt vmcnt(30)
	v_mfma_f32_32x32x2_f32 v[0:15], v87, v71, v[0:15]
	s_waitcnt vmcnt(29)
	v_mfma_f32_32x32x2_f32 v[0:15], v88, v72, v[0:15]
	s_waitcnt vmcnt(28)
	v_mfma_f32_32x32x2_f32 v[0:15], v89, v73, v[0:15]
	s_waitcnt vmcnt(27)
	v_mfma_f32_32x32x2_f32 v[0:15], v90, v74, v[0:15]
	s_waitcnt vmcnt(26)
	v_mfma_f32_32x32x2_f32 v[0:15], v91, v75, v[0:15]
	s_waitcnt vmcnt(25)
	v_mfma_f32_32x32x2_f32 v[0:15], v92, v76, v[0:15]
	s_waitcnt vmcnt(24)
	v_mfma_f32_32x32x2_f32 v[0:15], v93, v77, v[0:15]
	s_waitcnt vmcnt(23)
	v_mfma_f32_32x32x2_f32 v[0:15], v94, v78, v[0:15]
	s_waitcnt vmcnt(22)
	v_mfma_f32_32x32x2_f32 v[0:15], v95, v79, v[0:15]
	s_waitcnt vmcnt(21)
	v_mfma_f32_32x32x2_f32 v[0:15], v96, v80, v[0:15]
	s_waitcnt vmcnt(20)
	v_mfma_f32_32x32x2_f32 v[0:15], v97, v81, v[0:15]
	s_waitcnt vmcnt(19)
	v_mfma_f32_32x32x2_f32 v[0:15], v98, v82, v[0:15]
	s_waitcnt vmcnt(18)
	v_mfma_f32_32x32x2_f32 v[0:15], v99, v83, v[0:15]
	s_waitcnt vmcnt(17)
	v_mfma_f32_32x32x2_f32 v[0:15], v100, v84, v[0:15]
	s_waitcnt vmcnt(16)
	v_mfma_f32_32x32x2_f32 v[0:15], v101, v85, v[0:15]
	s_cmp_eq_u32 s34, 0xa80000
	s_cbranch_scc0 .LBB0_30
; #define LAS __attribute__((address_space(3)))
; __device__ __forceinline__ void phase0(CArgsP a, int l, LAS unsigned char* lds) {
;     ...
; #pragma unroll 16
;             for (int i = 0; i < 128; ++i) acc = __builtin_amdgcn_mfma_f32_32x32x2f32(Sp[i * 34], __builtin_nontemporal_load(W + (size_t)i * 2 * 12288), acc, 0, 0, 0);
;             {
;                 LAS float* Rw = RED + wave * 17 * 32 + l32;
; #pragma unroll
;                 for (int r = 0; r < 9; ++r) { const int row = (r & 3) + 8 * (r >> 2) + 4 * half; if (row < 17) Rw[row * 32] = acc[r]; }
;             }
;             __syncthreads();
;             for (int o = tid; o < 17 * 32; o += 512) { float sm = a->in[I_BMOD][ll * 12288 + n0 + (o & 31)];
; #pragma unroll
;                 for (int w = 0; w < 8; ++w) sm += RED[w * 17 * 32 + o];
;                 MOD[(size_t)(ll * 17 + (o >> 5)) * 12288 + n0 + (o & 31)] = sm; }
	v_lshl_add_u64 v[102:103], v[24:25], 0, s[34:35]
	global_load_dword v70, v[102:103], off nt
	v_add_co_u32_e64 v102, s[44:45], s52, v102
	s_nop 1
	v_addc_co_u32_e64 v103, s[44:45], 0, v103, s[44:45]
	global_load_dword v71, v[102:103], off nt
	v_add_co_u32_e64 v102, s[44:45], s52, v102
	s_nop 1
	v_addc_co_u32_e64 v103, s[44:45], 0, v103, s[44:45]
	global_load_dword v72, v[102:103], off nt
	v_add_co_u32_e64 v102, s[44:45], s52, v102
	s_nop 1
	v_addc_co_u32_e64 v103, s[44:45], 0, v103, s[44:45]
	global_load_dword v73, v[102:103], off nt
	v_add_co_u32_e64 v102, s[44:45], s52, v102
	s_nop 1
	v_addc_co_u32_e64 v103, s[44:45], 0, v103, s[44:45]
	global_load_dword v74, v[102:103], off nt
	v_add_co_u32_e64 v102, s[44:45], s52, v102
	s_nop 1
	v_addc_co_u32_e64 v103, s[44:45], 0, v103, s[44:45]
	global_load_dword v75, v[102:103], off nt
	v_add_co_u32_e64 v102, s[44:45], s52, v102
	s_nop 1
	v_addc_co_u32_e64 v103, s[44:45], 0, v103, s[44:45]
	global_load_dword v76, v[102:103], off nt
	v_add_co_u32_e64 v102, s[44:45], s52, v102
	s_nop 1
	v_addc_co_u32_e64 v103, s[44:45], 0, v103, s[44:45]
	global_load_dword v77, v[102:103], off nt
	v_add_co_u32_e64 v102, s[44:45], s52, v102
	s_nop 1
	v_addc_co_u32_e64 v103, s[44:45], 0, v103, s[44:45]
	global_load_dword v78, v[102:103], off nt
	v_add_co_u32_e64 v102, s[44:45], s52, v102
	s_nop 1
	v_addc_co_u32_e64 v103, s[44:45], 0, v103, s[44:45]
	global_load_dword v79, v[102:103], off nt
	v_add_co_u32_e64 v102, s[44:45], s52, v102
	s_nop 1
	v_addc_co_u32_e64 v103, s[44:45], 0, v103, s[44:45]
	global_load_dword v80, v[102:103], off nt
	v_add_co_u32_e64 v102, s[44:45], s52, v102
	s_nop 1
	v_addc_co_u32_e64 v103, s[44:45], 0, v103, s[44:45]
	global_load_dword v81, v[102:103], off nt
	v_add_co_u32_e64 v102, s[44:45], s52, v102
	s_nop 1
	v_addc_co_u32_e64 v103, s[44:45], 0, v103, s[44:45]
	global_load_dword v82, v[102:103], off nt
	v_add_co_u32_e64 v102, s[44:45], s52, v102
	s_nop 1
	v_addc_co_u32_e64 v103, s[44:45], 0, v103, s[44:45]
	global_load_dword v83, v[102:103], off nt
	v_add_co_u32_e64 v102, s[44:45], s52, v102
	s_nop 1
	v_addc_co_u32_e64 v103, s[44:45], 0, v103, s[44:45]
	global_load_dword v84, v[102:103], off nt
	v_add_co_u32_e64 v102, s[44:45], s52, v102
	s_nop 1
	v_addc_co_u32_e64 v103, s[44:45], 0, v103, s[44:45]
	global_load_dword v85, v[102:103], off nt
	s_add_u32 s34, s34, 0x180000
	s_addc_u32 s35, s35, 0
	ds_read2_b32 v[86:87], v28 offset1:34
	ds_read2_b32 v[88:89], v28 offset0:68 offset1:102
	ds_read2_b32 v[90:91], v28 offset0:136 offset1:170
	ds_read2_b32 v[92:93], v28 offset0:204 offset1:238
	v_add_u32_e32 v104, 0x400, v28
	ds_read2_b32 v[94:95], v104 offset0:16 offset1:50
	ds_read2_b32 v[96:97], v104 offset0:84 offset1:118
	ds_read2_b32 v[98:99], v104 offset0:152 offset1:186
	ds_read2_b32 v[100:101], v104 offset0:220 offset1:254
	v_add_u32_e32 v28, 0x880, v28
	s_waitcnt lgkmcnt(0)
	s_waitcnt vmcnt(31)
	v_mfma_f32_32x32x2_f32 v[0:15], v86, v54, v[0:15]
	s_waitcnt vmcnt(30)
	v_mfma_f32_32x32x2_f32 v[0:15], v87, v55, v[0:15]
	s_waitcnt vmcnt(29)
	v_mfma_f32_32x32x2_f32 v[0:15], v88, v56, v[0:15]
	s_waitcnt vmcnt(28)
	v_mfma_f32_32x32x2_f32 v[0:15], v89, v57, v[0:15]
	s_waitcnt vmcnt(27)
	v_mfma_f32_32x32x2_f32 v[0:15], v90, v58, v[0:15]
	s_waitcnt vmcnt(26)
	v_mfma_f32_32x32x2_f32 v[0:15], v91, v59, v[0:15]
	s_waitcnt vmcnt(25)
	v_mfma_f32_32x32x2_f32 v[0:15], v92, v60, v[0:15]
	s_waitcnt vmcnt(24)
	v_mfma_f32_32x32x2_f32 v[0:15], v93, v61, v[0:15]
	s_waitcnt vmcnt(23)
	v_mfma_f32_32x32x2_f32 v[0:15], v94, v62, v[0:15]
	s_waitcnt vmcnt(22)
	v_mfma_f32_32x32x2_f32 v[0:15], v95, v63, v[0:15]
	s_waitcnt vmcnt(21)
	v_mfma_f32_32x32x2_f32 v[0:15], v96, v64, v[0:15]
	s_waitcnt vmcnt(20)
	v_mfma_f32_32x32x2_f32 v[0:15], v97, v65, v[0:15]
	s_waitcnt vmcnt(19)
	v_mfma_f32_32x32x2_f32 v[0:15], v98, v66, v[0:15]
	s_waitcnt vmcnt(18)
	v_mfma_f32_32x32x2_f32 v[0:15], v99, v67, v[0:15]
	s_waitcnt vmcnt(17)
	v_mfma_f32_32x32x2_f32 v[0:15], v100, v68, v[0:15]
	s_waitcnt vmcnt(16)
	v_mfma_f32_32x32x2_f32 v[0:15], v101, v69, v[0:15]
	ds_read2_b32 v[86:87], v28 offset1:34
	ds_read2_b32 v[88:89], v28 offset0:68 offset1:102
	ds_read2_b32 v[90:91], v28 offset0:136 offset1:170
	ds_read2_b32 v[92:93], v28 offset0:204 offset1:238
	v_add_u32_e32 v104, 0x400, v28
	ds_read2_b32 v[94:95], v104 offset0:16 offset1:50
	ds_read2_b32 v[96:97], v104 offset0:84 offset1:118
	ds_read2_b32 v[98:99], v104 offset0:152 offset1:186
	ds_read2_b32 v[100:101], v104 offset0:220 offset1:254
	v_add_u32_e32 v28, 0x880, v28
	s_waitcnt lgkmcnt(0)
	s_waitcnt vmcnt(15)
	v_mfma_f32_32x32x2_f32 v[0:15], v86, v70, v[0:15]
	s_waitcnt vmcnt(14)
	v_mfma_f32_32x32x2_f32 v[0:15], v87, v71, v[0:15]
	s_waitcnt vmcnt(13)
	v_mfma_f32_32x32x2_f32 v[0:15], v88, v72, v[0:15]
	s_waitcnt vmcnt(12)
	v_mfma_f32_32x32x2_f32 v[0:15], v89, v73, v[0:15]
	s_waitcnt vmcnt(11)
	v_mfma_f32_32x32x2_f32 v[0:15], v90, v74, v[0:15]
	s_waitcnt vmcnt(10)
	v_mfma_f32_32x32x2_f32 v[0:15], v91, v75, v[0:15]
	s_waitcnt vmcnt(9)
	v_mfma_f32_32x32x2_f32 v[0:15], v92, v76, v[0:15]
	s_waitcnt vmcnt(8)
	v_mfma_f32_32x32x2_f32 v[0:15], v93, v77, v[0:15]
	s_waitcnt vmcnt(7)
	v_mfma_f32_32x32x2_f32 v[0:15], v94, v78, v[0:15]
	s_waitcnt vmcnt(6)
	v_mfma_f32_32x32x2_f32 v[0:15], v95, v79, v[0:15]
	s_waitcnt vmcnt(5)
	v_mfma_f32_32x32x2_f32 v[0:15], v96, v80, v[0:15]
	s_waitcnt vmcnt(4)
	v_mfma_f32_32x32x2_f32 v[0:15], v97, v81, v[0:15]
	s_waitcnt vmcnt(3)
	v_mfma_f32_32x32x2_f32 v[0:15], v98, v82, v[0:15]
	s_waitcnt vmcnt(2)
	v_mfma_f32_32x32x2_f32 v[0:15], v99, v83, v[0:15]
	s_waitcnt vmcnt(1)
	v_mfma_f32_32x32x2_f32 v[0:15], v100, v84, v[0:15]
	s_waitcnt vmcnt(0)
	v_mfma_f32_32x32x2_f32 v[0:15], v101, v85, v[0:15]
	s_nop 0
	s_nop 15
	s_nop 0
	ds_write2_b32 v27, v0, v1 offset1:32
	ds_write2_b32 v27, v2, v3 offset0:64 offset1:96
	v_add_u32_e32 v0, 0x400, v27
	ds_write2_b32 v0, v4, v5 offset1:32
	ds_write2_b32 v0, v6, v7 offset0:64 offset1:96
	s_and_saveexec_b64 s[34:35], s[42:43]
	ds_write_b32 v17, v8 offset:2048
	s_or_b64 exec, exec, s[34:35]
	s_waitcnt lgkmcnt(0)
	s_barrier
	s_and_saveexec_b64 s[34:35], vcc
	s_cbranch_execz .LBB0_28
	s_load_dwordx2 s[40:41], s[0:1], 0x38
	s_mul_i32 s44, s29, 0x3000
	s_add_i32 s44, s44, s30
	v_or_b32_e32 v0, s44, v18
	v_ashrrev_i32_e32 v1, 31, v0
	s_mul_i32 s29, s29, 17
	s_waitcnt lgkmcnt(0)
	v_lshl_add_u64 v[0:1], v[0:1], 2, s[40:41]
	v_lshl_add_u64 v[2:3], s[30:31], 2, v[22:23]
	s_mov_b64 s[30:31], 0
	v_mov_b32_e32 v4, v26
	v_mov_b32_e32 v5, v16
